# diff loop pinned to 64B (.p2align 6); natten mask batched loads
# speedup vs baseline: 1.0454x; 1.0454x over previous
; template <int DQK, int DV, int NAT, int VSHIFT, int COMB> ...
;     ...
;         for (int kt = 0; kt < nkt; kt += 2) {
;             ATT_STEP(sA0, sA1, sB0, sB1, kt, 0);
;             if (kt + 1 < nkt) ATT_STEP(sB0, sB1, sA0, sA1, kt + 1, 1);
;         }
.Ldpre_skip:
	.p2align 6
